# grid barrier: L1 invalidate before polling on both paths, and the XCD leader no longer waits for the ack of its generation-word atomic before resuming
# speedup vs baseline: 1.0003x; 1.0003x over previous
; #define PP (kp_get())
; DI unsigned xb_ld(unsigned* p)              { return __hip_atomic_load(p, __ATOMIC_RELAXED, __HIP_MEMORY_SCOPE_AGENT); }
; #define XB_SPIN(cond, bar) do { unsigned _sp = 0; while (cond) { __builtin_amdgcn_s_sleep(1); \
;     if ((++_sp & 255u) == 0u) { if (xb_ld(&(bar)[XB_TMO])) break; if (_sp > XB_SPIN_CAP) { atomicAdd(&(bar)[XB_TMO], 1u); break; } } } } while (0)
; DI void xcd_barrier(const XcdBarrier& b) {
;     ...
;             asm volatile("s_waitcnt vmcnt(0)" ::: "memory");
;         } else {
;             XB_SPIN(xb_ld(&bar[XB_XGEN(b.x)]) == gen, bar);
;             __builtin_amdgcn_fence(__ATOMIC_ACQUIRE, "agent");
;             asm volatile("s_waitcnt vmcnt(0)" ::: "memory");
;         }
;     }
;     __syncthreads();
; __global__ void __launch_bounds__(512, 2) fwd_megakernel(Params P) {
;     ...
;         { pg8::Gemm g{HBUF, (const bf16_t*)(PP->ws + WS_WIN), DM, DM, DM, 0, 0}; pg8::SchedMN S{MTOK / 256, NINA / 256, G, c};
;           pg8::EpiInProj E{PP->ws, (const f32x2_t*)(PP->ws + WS_ROPE), (const float*)(PP->ws + WS_PART)}; pg8::gemm_phase(lds, g, S, E); }
.LBB0_174:
	s_or_b64 exec, exec, s[38:39]
.LBB0_175:
	s_or_b64 exec, exec, s[30:31]
	s_mov_b64 s[12:13], s[0:1]
	s_waitcnt lgkmcnt(0)
	s_barrier
	s_load_dwordx2 s[36:37], s[12:13], 0xe0
	s_mov_b64 s[12:13], s[0:1]
	s_load_dwordx2 s[44:45], s[12:13], 0xe0
	s_mov_b64 s[12:13], s[0:1]
	s_load_dwordx2 s[62:63], s[12:13], 0xe0
	s_mov_b64 s[12:13], s[0:1]
	s_load_dwordx2 s[30:31], s[12:13], 0xe0
	s_mov_b64 s[12:13], s[0:1]
	s_load_dwordx2 s[38:39], s[12:13], 0xe0
	v_readlane_b32 s12, v252, 16
	v_readlane_b32 s13, v252, 17
	v_mov_b32_e32 v0, v196
	s_andn2_b64 vcc, exec, s[12:13]
	v_cndmask_b32_e64 v2, 0, 1, s[12:13]
	v_cmp_ne_u32_e64 s[68:69], 1, v2
	v_readfirstlane_b32 s14, v0
	s_cbranch_vccnz .LBB0_177
	v_readlane_b32 s12, v253, 41
	s_mov_b32 s64, s12
	v_readlane_b32 s12, v253, 40
	s_mov_b32 s66, s12

;     DI bool next(int i, Unit& u) const { const long L = (long)i * G + c; if (L >= (long)nM * nN) return false; tile_decode((int)L, nM, nN, u.pm, u.pn); u.z = 0; return true; }
; #define PG8_WAIT_V(n) asm volatile("s_waitcnt vmcnt(" #n ")" ::: "memory")
; template <class Epi, class Sched>
; DI void gemm_phase(LAS unsigned char* lds, const Gemm g, const Sched& S, const Epi& E) {
;     ...
;     for (int i = 0; i < 2; ++i) { int R, C; stage_rc(tid * 16 + i * 8192, R, C); const int Rb = (R & ~31) + perm32(R & 31);
;         voffA[i] = (unsigned)(R * g.lda + C) * 2u; voffB[i] = (unsigned)(Rb * g.ldb + C) * 2u; }
;     const size_t kstep = (size_t)(BK * 2);
;     const size_t hstepA = (size_t)HALF * g.lda * 2, hstepB = (size_t)HALF * g.ldb * 2;
;     const unsigned ldsw = (unsigned)wid * 1024u;
;     const int aoff = lds_byte(wr * 64 + fr, fq * 8), boff = lds_byte(wc * 32 + fr, fq * 8);
;     ...
;     Unit cur, nxt; int ui = 0;
;     if (!S.next(0, cur)) return;
;     ...
;     if constexpr (Epi::NEEDS_R) {
;         Unit uu; for (int i = 0; i < 8 && S.next(i, uu); ++i) PG8_RFILL(uu, i);
;     }
;     f32x4 acc[2][2][4][2];
; #pragma unroll
;     for (int a = 0; a < 2; ++a)
; #pragma unroll
;         for (int b = 0; b < 2; ++b)
; #pragma unroll
;             for (int m = 0; m < 4; ++m)
; #pragma unroll
;                 for (int n = 0; n < 2; ++n) acc[a][b][m][n] = (f32x4){0.f, 0.f, 0.f, 0.f};
;     bf16x8 At[4][2], B0[2][2], B1[2][2];
;     const char* cA = (const char*)g.A + (size_t)cur.z * g.zA * 2 + (size_t)cur.pm * 2 * hstepA;
;     const char* cB = (const char*)g.Bt + (size_t)cur.z * g.zB * 2 + (size_t)cur.pn * 2 * hstepB;
;     PG8_STAGE(PG8_SB(0, 0), cB, voffB); PG8_STAGE(PG8_SB(0, 1), cB + hstepB, voffB); PG8_STAGE(PG8_SA(0, 0), cA, voffA); PG8_STAGE(PG8_SA(0, 1), cA + hstepA, voffA);
;     if (wr == 1) PG8_BAR;
;     PG8_WAIT_V(2); PG8_BAR;
;     PG8_STAGE(PG8_SB(1, 0), cB + kstep, voffB); PG8_STAGE(PG8_SA(1, 0), cA + kstep, voffA); PG8_STAGE(PG8_SB(1, 1), cB + hstepB + kstep, voffB);
; __global__ void __launch_bounds__(512, 2) fwd_megakernel(Params P) {
;     ...
;         xcd_barrier(xbar);
;         { pg8::Gemm g{(const bf16_t*)(PP->ws + WS_A2), (const bf16_t*)(PP->ws + WS_WST), SSM_K2, 512, 512, (long)SSM_M2 * SSM_K2, (long)256 * 512};
;           pg8::SchedZ S{32, SSM_M2 / 256, 1, G, c}; pg8::EpiSloc E{(float*)(PP->ws + WS_SLOC)}; pg8::gemm_phase(lds, g, S, E); }
.LBB0_429:
	s_or_b64 exec, exec, s[38:39]
.LBB0_430:
	s_or_b64 exec, exec, s[30:31]
	v_readlane_b32 s12, v252, 41
	s_mov_b64 s[38:39], s[0:1]
	s_mov_b64 s[36:37], s[0:1]
	s_mov_b64 s[30:31], s[0:1]
	v_mov_b32_e32 v18, v196
	v_readlane_b32 s13, v252, 42
	s_waitcnt lgkmcnt(0)
	s_barrier
	s_andn2_b64 vcc, exec, s[12:13]
	v_readfirstlane_b32 s40, v18
	s_cbranch_vccnz .LBB0_448
	v_lshlrev_b32_e32 v0, 4, v18
	v_add_u32_e32 v2, 0x2000, v0
	v_ashrrev_i32_e32 v3, 31, v2
	v_lshrrev_b32_e32 v3, 22, v3
	v_add_u32_e32 v3, v2, v3
	v_ashrrev_i32_e32 v10, 10, v3
	v_mul_i32_i24_e32 v3, 0x400, v10
	v_sub_u32_e32 v2, v2, v3
	v_lshrrev_b32_e32 v3, 4, v2
	v_bitop3_b32 v2, v3, v2, 32 bitop3:0x6c
	v_ashrrev_i32_e32 v3, 31, v2
	v_lshrrev_b32_e32 v3, 26, v3
	v_add_u32_e32 v3, v2, v3
	v_lshlrev_b32_e32 v4, 3, v10
	v_ashrrev_i32_e32 v11, 6, v3
	v_and_b32_e32 v4, -16, v4
	v_add_u32_e32 v4, v11, v4
	v_and_b32_e32 v5, 3, v11
	s_mov_b32 s17, 0x3fffe0
	v_lshrrev_b32_e32 v6, 2, v4
	v_lshlrev_b32_e32 v7, 1, v4
	v_and_b32_e32 v3, 0xc0, v3
	v_and_or_b32 v5, v4, s17, v5
	v_and_b32_e32 v6, 4, v6
	v_and_b32_e32 v7, 24, v7
	v_sub_u32_e32 v2, v2, v3
	v_or3_b32 v5, v5, v6, v7
	v_lshlrev_b32_e32 v6, 5, v10
	v_ashrrev_i16_sdwa v2, v250, sext(v2) dst_sel:DWORD dst_unused:UNUSED_PAD src0_sel:DWORD src1_sel:BYTE_0
	v_and_b32_e32 v12, 32, v6
	v_bfe_i32 v13, v2, 0, 16
	v_add_u32_e32 v2, v12, v13
	v_lshlrev_b32_e32 v3, 1, v2
	s_movk_i32 s25, 0x280
	v_lshl_add_u32 v66, v5, 10, v3
	v_mul_lo_u32 v3, v4, s25
	v_add_lshl_u32 v68, v2, v3, 1
	v_bfe_i32 v2, v18, 27, 1
	v_lshrrev_b32_e32 v2, 22, v2
	v_add_u32_e32 v2, v0, v2
	v_and_b32_e32 v2, 0xfffffc00, v2
	v_sub_u32_e32 v0, v0, v2
	v_lshrrev_b32_e32 v2, 4, v0
	v_bitop3_b32 v2, v2, v0, 32 bitop3:0x6c
	v_ashrrev_i32_e32 v0, 31, v0
	v_lshrrev_b32_e32 v0, 26, v0
	v_add_u32_e32 v0, v2, v0
	v_ashrrev_i32_e32 v14, 6, v0
	v_ashrrev_i32_e32 v0, 31, v18
	v_lshrrev_b32_e32 v0, 26, v0
	v_add_u32_e32 v0, v18, v0
	v_ashrrev_i32_e32 v15, 6, v0
	v_lshlrev_b32_e32 v0, 3, v15
	s_load_dwordx2 s[12:13], s[38:39], 0xe0
	s_load_dwordx2 s[14:15], s[36:37], 0xe0
	v_and_b32_e32 v0, -16, v0
	v_add_u32_e32 v3, v14, v0
	v_and_b32_e32 v0, 3, v14
	v_lshrrev_b32_e32 v4, 2, v3
	v_lshlrev_b32_e32 v5, 1, v3
	v_and_or_b32 v0, v3, s17, v0
	v_and_b32_e32 v4, 4, v4
	v_and_b32_e32 v5, 24, v5
	s_waitcnt lgkmcnt(0)
	s_add_u32 s12, s12, 0x17a00000
	v_or3_b32 v0, v0, v4, v5
	v_lshlrev_b32_e32 v4, 5, v15
	s_addc_u32 s13, s13, 0
	v_and_b32_e32 v16, 32, v4
	v_mul_i32_i24_e32 v4, 64, v14
	s_add_u32 s14, s14, 0x3d00000
	v_sub_u32_e32 v2, v2, v4
	s_addc_u32 s15, s15, 0
	s_ashr_i32 s41, s40, 6
	v_ashrrev_i16_sdwa v2, v250, sext(v2) dst_sel:DWORD dst_unused:UNUSED_PAD src0_sel:DWORD src1_sel:BYTE_0
	s_ashr_i32 s44, s40, 8
	s_lshl_b32 s16, s41, 10
	v_bfe_i32 v17, v2, 0, 16
	v_readlane_b32 s36, v252, 48
	v_add_u32_e32 v2, v16, v17
	v_readlane_b32 s37, v252, 49
	s_add_u32 s38, s14, s36
	v_lshlrev_b32_e32 v4, 1, v2
	s_addc_u32 s39, s15, s37
	s_add_i32 s17, s16, 0
	v_lshl_add_u32 v0, v0, 10, v4
	s_add_i32 m0, s17, 0x10000
	v_readlane_b32 s36, v252, 46
	v_mul_lo_u32 v3, v3, s25
	global_load_lds_dwordx4 v0, s[38:39]
	s_add_i32 m0, s17, 0x12000
	s_mul_i32 s25, s36, 0x140000
	s_add_u32 s45, s12, s25
	s_mul_hi_i32 s25, s36, 0x140000
	s_addc_u32 s50, s13, s25
	v_readlane_b32 s37, v252, 47
	s_add_u32 s36, s38, 0x20000
	s_addc_u32 s37, s39, 0
	s_add_i32 s25, s17, 0x14000
	global_load_lds_dwordx4 v66, s[38:39]
	s_mov_b32 m0, s25
	s_add_i32 s28, s17, 0x16000
	global_load_lds_dwordx4 v0, s[36:37]
	s_mov_b32 m0, s28
	v_add_lshl_u32 v70, v2, v3, 1
	global_load_lds_dwordx4 v66, s[36:37]
	v_readlane_b32 s36, v252, 44
	s_add_u32 s62, s45, s36
	v_readlane_b32 s36, v252, 45
	s_addc_u32 s63, s50, s36
	s_add_i32 s66, s17, 0x2000
	s_mov_b32 m0, s17
	s_add_u32 s36, s62, 0x28000
	global_load_lds_dwordx4 v70, s[62:63]
	s_mov_b32 m0, s66
	s_addc_u32 s37, s63, 0
	s_add_i32 s67, s17, 0x4000
	global_load_lds_dwordx4 v68, s[62:63]
	s_mov_b32 m0, s67
	s_add_i32 s70, s17, 0x6000
	global_load_lds_dwordx4 v70, s[36:37]
	s_mov_b32 m0, s70
	v_mov_b32_e32 v67, v1
	global_load_lds_dwordx4 v68, s[36:37]
	s_load_dwordx2 s[36:37], s[30:31], 0xe0
	v_mov_b32_e32 v71, v1
	v_mov_b32_e32 v69, v1
	s_cmp_eq_u32 s44, 1
	v_lshl_add_u64 v[8:9], s[38:39], 0, v[0:1]
	v_lshl_add_u64 v[6:7], s[38:39], 0, v[66:67]
	v_lshl_add_u64 v[2:3], s[62:63], 0, v[70:71]
	s_cselect_b64 s[30:31], -1, 0
	s_cmp_lg_u32 s44, 1
	v_lshl_add_u64 v[4:5], s[62:63], 0, v[68:69]
	s_cbranch_scc1 .LBB0_433
	s_barrier

; #define LAS __attribute__((address_space(3)))
; DI int opaque(int v) { asm volatile("" : "+v"(v)); return v; }
; #define PP (kp_get())
; DI void ssm_scan(LAS unsigned char* lds) {
;     const int tid = opaque(threadIdx.x);
;     const float* sloc = (const float*)(PP->ws + WS_SLOC); bf16_t* a2 = (bf16_t*)(PP->ws + WS_A2); const f32x2_t* lamT = (const f32x2_t*)(PP->ws + WS_LAMT);
;     for (int un = blockIdx.x; un < NB * 32; un += gridDim.x) {
;         const int g = un & 31, b = un >> 5; const size_t r0 = (size_t)g * SSM_M2 + b * SSM_NC;
;         const f32x4* src = (const f32x4*)(sloc + r0 * 128) + tid;
; #pragma unroll
;         for (int j = 0; j < 8; ++j) ((LAS f32x4*)lds)[tid + j * 512] = src[j * 512];
;         __syncthreads();
;         if (tid < 64) { const int p = tid; const f32x2_t lt = lamT[g * 64 + p]; float sr = 0.f, si = 0.f; const LAS float* L = (const LAS float*)lds;
; __global__ void __launch_bounds__(512, 2) fwd_megakernel(Params P) {
;     ...
;         xcd_barrier(xbar);
;         ssm_scan(lds);
.LBB0_499:
	s_or_b64 exec, exec, s[38:39]
.LBB0_500:
	s_or_b64 exec, exec, s[30:31]
	v_readlane_b32 s12, v252, 50
	v_readlane_b32 s13, v252, 51
	s_waitcnt lgkmcnt(0)
	v_mov_b32_e32 v2, v196
	s_mov_b64 s[30:31], s[0:1]
	v_cndmask_b32_e64 v0, 0, 1, s[12:13]
	s_mov_b64 s[36:37], s[0:1]
	s_mov_b64 s[38:39], s[0:1]
	v_cmp_ne_u32_e64 s[94:95], 1, v0
	s_andn2_b64 vcc, exec, s[12:13]
	s_barrier
	s_cbranch_vccnz .LBB0_506
	s_load_dwordx2 s[12:13], s[38:39], 0xe0
	s_load_dwordx2 s[14:15], s[30:31], 0xe0
	s_load_dwordx2 s[16:17], s[36:37], 0xe0
	v_ashrrev_i32_e32 v3, 31, v2
	v_lshl_add_u32 v0, v2, 4, 0
	s_waitcnt lgkmcnt(0)
	s_add_u32 s30, s12, 0x300000
	v_lshl_add_u64 v[4:5], v[2:3], 4, s[14:15]
	s_addc_u32 s31, s13, 0
	s_mov_b64 s[12:13], 0x1a200000
	v_lshl_add_u64 v[4:5], v[4:5], 0, s[12:13]
	v_cmp_gt_i32_e64 s[84:85], 64, v2
	v_lshl_add_u32 v18, v2, 2, 0
	v_lshl_add_u64 v[6:7], v[2:3], 1, s[16:17]
	v_readlane_b32 s12, v255, 3
	s_mov_b32 s13, s2
	s_mov_b32 s14, s2
	s_branch .LBB0_503

;     DI bool next(int i, Unit& u) const { const long L = (long)i * G + c; if (L >= (long)nM * nN) return false; tile_decode((int)L, nM, nN, u.pm, u.pn); u.z = 0; return true; }
; #define PG8_WAIT_V(n) asm volatile("s_waitcnt vmcnt(" #n ")" ::: "memory")
; template <class Epi, class Sched>
; DI void gemm_phase(LAS unsigned char* lds, const Gemm g, const Sched& S, const Epi& E) {
;     ...
;     for (int i = 0; i < 2; ++i) { int R, C; stage_rc(tid * 16 + i * 8192, R, C); const int Rb = (R & ~31) + perm32(R & 31);
;         voffA[i] = (unsigned)(R * g.lda + C) * 2u; voffB[i] = (unsigned)(Rb * g.ldb + C) * 2u; }
;     const size_t kstep = (size_t)(BK * 2);
;     const size_t hstepA = (size_t)HALF * g.lda * 2, hstepB = (size_t)HALF * g.ldb * 2;
;     const unsigned ldsw = (unsigned)wid * 1024u;
;     const int aoff = lds_byte(wr * 64 + fr, fq * 8), boff = lds_byte(wc * 32 + fr, fq * 8);
;     ...
;     Unit cur, nxt; int ui = 0;
;     if (!S.next(0, cur)) return;
;     ...
;     if constexpr (Epi::NEEDS_R) {
;         Unit uu; for (int i = 0; i < 8 && S.next(i, uu); ++i) PG8_RFILL(uu, i);
;     }
;     f32x4 acc[2][2][4][2];
; #pragma unroll
;     for (int a = 0; a < 2; ++a)
; #pragma unroll
;         for (int b = 0; b < 2; ++b)
; #pragma unroll
;             for (int m = 0; m < 4; ++m)
; #pragma unroll
;                 for (int n = 0; n < 2; ++n) acc[a][b][m][n] = (f32x4){0.f, 0.f, 0.f, 0.f};
;     bf16x8 At[4][2], B0[2][2], B1[2][2];
;     const char* cA = (const char*)g.A + (size_t)cur.z * g.zA * 2 + (size_t)cur.pm * 2 * hstepA;
;     const char* cB = (const char*)g.Bt + (size_t)cur.z * g.zB * 2 + (size_t)cur.pn * 2 * hstepB;
;     PG8_STAGE(PG8_SB(0, 0), cB, voffB); PG8_STAGE(PG8_SB(0, 1), cB + hstepB, voffB); PG8_STAGE(PG8_SA(0, 0), cA, voffA); PG8_STAGE(PG8_SA(0, 1), cA + hstepA, voffA);
;     if (wr == 1) PG8_BAR;
;     PG8_WAIT_V(2); PG8_BAR;
;     PG8_STAGE(PG8_SB(1, 0), cB + kstep, voffB); PG8_STAGE(PG8_SA(1, 0), cA + kstep, voffA); PG8_STAGE(PG8_SB(1, 1), cB + hstepB + kstep, voffB);
; __global__ void __launch_bounds__(512, 2) fwd_megakernel(Params P) {
;     ...
;         xcd_barrier(xbar);
;         { pg8::Gemm g{(const bf16_t*)(PP->ws + WS_A2), (const bf16_t*)(PP->ws + WS_TOEP), SSM_K2, SSM_K2, SSM_K2, (long)SSM_M2 * SSM_K2, (long)512 * SSM_K2};
;           pg8::SchedZ S{32, SSM_M2 / 256, 2, G, c}; pg8::EpiGelu E{(bf16_t*)(PP->ws + WS_YACT)}; pg8::gemm_phase(lds, g, S, E); }
.LBB0_557:
	s_or_b64 exec, exec, s[38:39]
.LBB0_558:
	s_or_b64 exec, exec, s[30:31]
	s_mov_b64 s[36:37], s[0:1]
	s_mov_b64 s[30:31], s[0:1]
	s_mov_b64 s[38:39], s[0:1]
	v_mov_b32_e32 v0, v196
	s_waitcnt lgkmcnt(0)
	s_barrier
	s_and_b64 vcc, exec, s[94:95]
	v_readfirstlane_b32 s14, v0
	s_cbranch_vccnz .LBB0_578
	v_lshlrev_b32_e32 v2, 4, v0
	v_add_u32_e32 v3, 0x2000, v2
	v_ashrrev_i32_e32 v4, 31, v3
	v_lshrrev_b32_e32 v4, 22, v4
	v_add_u32_e32 v4, v3, v4
	v_ashrrev_i32_e32 v10, 10, v4
	v_mul_i32_i24_e32 v4, 0x400, v10
	v_sub_u32_e32 v3, v3, v4
	v_lshrrev_b32_e32 v4, 4, v3
	v_bitop3_b32 v3, v4, v3, 32 bitop3:0x6c
	s_load_dwordx2 s[12:13], s[36:37], 0xe0
	s_load_dwordx2 s[16:17], s[30:31], 0xe0
	v_ashrrev_i32_e32 v4, 31, v3
	v_lshrrev_b32_e32 v4, 26, v4
	v_add_u32_e32 v4, v3, v4
	v_lshlrev_b32_e32 v5, 3, v10
	v_ashrrev_i32_e32 v11, 6, v4
	v_and_b32_e32 v5, -16, v5
	s_waitcnt lgkmcnt(0)
	s_add_u32 s25, s12, 0x17a00000
	v_add_u32_e32 v5, v11, v5
	s_addc_u32 s28, s13, 0
	v_and_b32_e32 v6, 3, v11
	s_mov_b32 s13, 0x1ffffe0
	v_lshrrev_b32_e32 v7, 2, v5
	v_lshlrev_b32_e32 v8, 1, v5
	v_and_b32_e32 v4, 0xc0, v4
	v_and_or_b32 v6, v5, s13, v6
	v_and_b32_e32 v7, 4, v7
	v_and_b32_e32 v8, 24, v8
	v_sub_u32_e32 v3, v3, v4
	v_or3_b32 v6, v6, v7, v8
	v_lshlrev_b32_e32 v7, 5, v10
	v_ashrrev_i16_sdwa v3, v250, sext(v3) dst_sel:DWORD dst_unused:UNUSED_PAD src0_sel:DWORD src1_sel:BYTE_0
	s_movk_i32 s12, 0x280
	v_and_b32_e32 v12, 32, v7
	v_bfe_i32 v13, v3, 0, 16
	v_mul_lo_u32 v6, v6, s12
	v_add_u32_e32 v3, v12, v13
	v_mul_lo_u32 v4, v5, s12
	v_add_lshl_u32 v130, v6, v3, 1
	v_add_lshl_u32 v132, v3, v4, 1
	v_bfe_i32 v3, v0, 27, 1
	v_lshrrev_b32_e32 v3, 22, v3
	v_add_u32_e32 v3, v2, v3
	v_and_b32_e32 v3, 0xfffffc00, v3
	v_sub_u32_e32 v2, v2, v3
	v_lshrrev_b32_e32 v3, 4, v2
	v_bitop3_b32 v3, v3, v2, 32 bitop3:0x6c
	v_ashrrev_i32_e32 v2, 31, v2
	v_lshrrev_b32_e32 v2, 26, v2
	v_add_u32_e32 v2, v3, v2
	v_ashrrev_i32_e32 v14, 6, v2
	v_ashrrev_i32_e32 v2, 31, v0
	v_lshrrev_b32_e32 v2, 26, v2
	v_add_u32_e32 v2, v0, v2
	v_ashrrev_i32_e32 v15, 6, v2
	v_lshlrev_b32_e32 v2, 3, v15
	v_and_b32_e32 v2, -16, v2
	v_add_u32_e32 v2, v14, v2
	v_and_b32_e32 v4, 3, v14
	v_lshrrev_b32_e32 v5, 2, v2
	v_lshlrev_b32_e32 v6, 1, v2
	s_add_u32 s40, s16, 0x4500000
	v_and_or_b32 v4, v2, s13, v4
	v_and_b32_e32 v5, 4, v5
	v_and_b32_e32 v6, 24, v6
	s_addc_u32 s41, s17, 0
	s_ashr_i32 s15, s14, 6
	v_or3_b32 v4, v4, v5, v6
	v_lshlrev_b32_e32 v5, 5, v15
	v_readlane_b32 s17, v253, 10
	s_ashr_i32 s16, s14, 8
	s_lshl_b32 s50, s15, 10
	v_mul_lo_u32 v4, v4, s12
	v_and_b32_e32 v16, 32, v5
	v_mul_i32_i24_e32 v5, 64, v14
	v_mul_lo_u32 v2, v2, s12
	s_mul_i32 s12, s17, 0xa0000
	v_sub_u32_e32 v3, v3, v5
	s_add_u32 s12, s40, s12
	s_mul_hi_i32 s13, s17, 0xa0000
	v_ashrrev_i16_sdwa v3, v250, sext(v3) dst_sel:DWORD dst_unused:UNUSED_PAD src0_sel:DWORD src1_sel:BYTE_0
	s_addc_u32 s13, s41, s13
	v_readlane_b32 s30, v253, 28
	v_bfe_i32 v17, v3, 0, 16
	s_add_u32 s36, s12, s30
	v_readlane_b32 s12, v253, 29
	v_add_u32_e32 v3, v16, v17
	s_addc_u32 s37, s13, s12
	s_add_i32 s12, s50, 0
	v_add_lshl_u32 v134, v4, v3, 1
	s_add_i32 m0, s12, 0x10000
	s_mul_i32 s13, s17, 0x140000
	global_load_lds_dwordx4 v134, s[36:37]
	s_add_i32 m0, s12, 0x12000
	s_add_u32 s13, s25, s13
	s_mul_hi_i32 s17, s17, 0x140000
	s_addc_u32 s17, s28, s17
	s_add_u32 s30, s36, 0x28000
	global_load_lds_dwordx4 v130, s[36:37]
	s_addc_u32 s31, s37, 0
	s_add_i32 m0, s12, 0x14000
	v_add_lshl_u32 v136, v3, v2, 1
	global_load_lds_dwordx4 v134, s[30:31]
	s_add_i32 m0, s12, 0x16000
	s_load_dwordx2 s[38:39], s[38:39], 0xe0
	global_load_lds_dwordx4 v130, s[30:31]
	v_readlane_b32 s31, v252, 52
	s_mul_i32 s30, s31, 0x50000
	s_add_u32 s30, s13, s30
	s_mul_hi_i32 s13, s31, 0x50000
	s_addc_u32 s31, s17, s13
	s_add_i32 s13, s12, 0x2000
	s_mov_b32 m0, s12
	s_add_u32 s44, s30, 0x28000
	global_load_lds_dwordx4 v136, s[30:31]
	s_mov_b32 m0, s13
	s_addc_u32 s45, s31, 0
	s_add_i32 s51, s12, 0x4000
	global_load_lds_dwordx4 v132, s[30:31]
	s_mov_b32 m0, s51
	s_add_i32 s72, s12, 0x6000
	global_load_lds_dwordx4 v136, s[44:45]
	s_mov_b32 m0, s72
	v_mov_b32_e32 v135, v1
	global_load_lds_dwordx4 v132, s[44:45]
	v_mov_b32_e32 v131, v1
	v_mov_b32_e32 v137, v1
	v_mov_b32_e32 v133, v1
	s_cmp_eq_u32 s16, 1
	v_lshl_add_u64 v[8:9], s[36:37], 0, v[134:135]
	v_lshl_add_u64 v[6:7], s[36:37], 0, v[130:131]
	v_lshl_add_u64 v[2:3], s[30:31], 0, v[136:137]
	s_cselect_b64 s[52:53], -1, 0
	s_cmp_lg_u32 s16, 1
	v_lshl_add_u64 v[4:5], s[30:31], 0, v[132:133]
	s_cbranch_scc1 .LBB0_561
	s_barrier

;     DI bool next(int i, Unit& u) const { const long L = (long)i * G + c; if (L >= (long)nM * nN) return false; tile_decode((int)L, nM, nN, u.pm, u.pn); u.z = 0; return true; }
; #define PG8_WAIT_V(n) asm volatile("s_waitcnt vmcnt(" #n ")" ::: "memory")
; #define PG8_BAR __builtin_amdgcn_s_barrier()
; template <class Epi, class Sched>
; DI void gemm_phase(LAS unsigned char* lds, const Gemm g, const Sched& S, const Epi& E) {
;     ...
;     for (int i = 0; i < 2; ++i) { int R, C; stage_rc(tid * 16 + i * 8192, R, C); const int Rb = (R & ~31) + perm32(R & 31);
;         voffA[i] = (unsigned)(R * g.lda + C) * 2u; voffB[i] = (unsigned)(Rb * g.ldb + C) * 2u; }
;     const size_t kstep = (size_t)(BK * 2);
;     const size_t hstepA = (size_t)HALF * g.lda * 2, hstepB = (size_t)HALF * g.ldb * 2;
;     const unsigned ldsw = (unsigned)wid * 1024u;
;     const int aoff = lds_byte(wr * 64 + fr, fq * 8), boff = lds_byte(wc * 32 + fr, fq * 8);
;     ...
;     Unit cur, nxt; int ui = 0;
;     if (!S.next(0, cur)) return;
;     ...
;     if constexpr (Epi::NEEDS_R) {
;         Unit uu; for (int i = 0; i < 8 && S.next(i, uu); ++i) PG8_RFILL(uu, i);
;     }
;     f32x4 acc[2][2][4][2];
; #pragma unroll
;     for (int a = 0; a < 2; ++a)
; #pragma unroll
;         for (int b = 0; b < 2; ++b)
; #pragma unroll
;             for (int m = 0; m < 4; ++m)
; #pragma unroll
;                 for (int n = 0; n < 2; ++n) acc[a][b][m][n] = (f32x4){0.f, 0.f, 0.f, 0.f};
;     bf16x8 At[4][2], B0[2][2], B1[2][2];
;     const char* cA = (const char*)g.A + (size_t)cur.z * g.zA * 2 + (size_t)cur.pm * 2 * hstepA;
;     const char* cB = (const char*)g.Bt + (size_t)cur.z * g.zB * 2 + (size_t)cur.pn * 2 * hstepB;
;     PG8_STAGE(PG8_SB(0, 0), cB, voffB); PG8_STAGE(PG8_SB(0, 1), cB + hstepB, voffB); PG8_STAGE(PG8_SA(0, 0), cA, voffA); PG8_STAGE(PG8_SA(0, 1), cA + hstepA, voffA);
;     if (wr == 1) PG8_BAR;
;     PG8_WAIT_V(2); PG8_BAR;
;     PG8_STAGE(PG8_SB(1, 0), cB + kstep, voffB); PG8_STAGE(PG8_SA(1, 0), cA + kstep, voffA); PG8_STAGE(PG8_SB(1, 1), cB + hstepB + kstep, voffB);
; __global__ void __launch_bounds__(512, 2) fwd_megakernel(Params P) {
;     ...
;         xcd_barrier(xbar);
;         { pg8::Gemm g{(const bf16_t*)(PP->ws + WS_YACT), (const bf16_t*)(PP->ws + WS_WGLU), 512, 512, 512, 0, 0}; pg8::SchedMN S{MTOK / 256, 4, G, c};
;           pg8::EpiGlu E{(bf16_t*)(PP->ws + WS_YSSM)}; pg8::gemm_phase(lds, g, S, E); }
.LBB0_629:
	s_or_b64 exec, exec, s[38:39]
.LBB0_630:
	s_or_b64 exec, exec, s[30:31]
	v_cmp_ne_u32_e64 s[12:13], 1, v245
	s_mov_b64 s[36:37], s[0:1]
	s_mov_b64 s[30:31], s[0:1]
	v_writelane_b32 v252, s12, 28
	s_mov_b64 s[38:39], s[0:1]
	v_mov_b32_e32 v16, v196
	v_writelane_b32 v252, s13, 29
	v_readlane_b32 s12, v251, 2
	v_readlane_b32 s13, v251, 3
	s_waitcnt lgkmcnt(0)
	s_barrier
	s_andn2_b64 vcc, exec, s[12:13]
	v_readfirstlane_b32 s45, v16
	s_cbranch_vccnz .LBB0_650
	v_lshlrev_b32_e32 v0, 4, v16
	v_add_u32_e32 v2, 0x2000, v0
	v_ashrrev_i32_e32 v3, 31, v2
	v_lshrrev_b32_e32 v3, 22, v3
	v_add_u32_e32 v3, v2, v3
	v_ashrrev_i32_e32 v10, 10, v3
	v_mul_i32_i24_e32 v3, 0x400, v10
	v_sub_u32_e32 v2, v2, v3
	v_lshrrev_b32_e32 v3, 4, v2
	v_bitop3_b32 v2, v3, v2, 32 bitop3:0x6c
	v_ashrrev_i32_e32 v3, 31, v2
	v_lshrrev_b32_e32 v3, 26, v3
	v_add_u32_e32 v3, v2, v3
	v_lshlrev_b32_e32 v4, 3, v10
	v_ashrrev_i32_e32 v11, 6, v3
	v_and_b32_e32 v4, -16, v4
	v_add_u32_e32 v4, v11, v4
	v_and_b32_e32 v5, 3, v11
	s_mov_b32 s17, 0x3fffe0
	v_lshrrev_b32_e32 v6, 2, v4
	v_lshlrev_b32_e32 v7, 1, v4
	v_and_b32_e32 v3, 0xc0, v3
	v_and_or_b32 v5, v4, s17, v5
	v_and_b32_e32 v6, 4, v6
	v_and_b32_e32 v7, 24, v7
	v_sub_u32_e32 v2, v2, v3
	v_or3_b32 v5, v5, v6, v7
	v_lshlrev_b32_e32 v6, 5, v10
	v_ashrrev_i16_sdwa v2, v250, sext(v2) dst_sel:DWORD dst_unused:UNUSED_PAD src0_sel:DWORD src1_sel:BYTE_0
	v_and_b32_e32 v6, 32, v6
	v_bfe_i32 v12, v2, 0, 16
	v_add_lshl_u32 v2, v6, v12, 1
	v_lshl_add_u32 v130, v5, 10, v2
	v_lshl_add_u32 v132, v4, 10, v2
	v_bfe_i32 v2, v16, 27, 1
	v_lshrrev_b32_e32 v2, 22, v2
	v_add_u32_e32 v2, v0, v2
	v_and_b32_e32 v2, 0xfffffc00, v2
	v_sub_u32_e32 v0, v0, v2
	v_lshrrev_b32_e32 v2, 4, v0
	v_bitop3_b32 v2, v2, v0, 32 bitop3:0x6c
	v_ashrrev_i32_e32 v0, 31, v0
	v_lshrrev_b32_e32 v0, 26, v0
	v_add_u32_e32 v0, v2, v0
	v_ashrrev_i32_e32 v13, 6, v0
	v_ashrrev_i32_e32 v0, 31, v16
	v_lshrrev_b32_e32 v0, 26, v0
	v_add_u32_e32 v0, v16, v0
	s_load_dwordx2 s[12:13], s[36:37], 0xe0
	s_load_dwordx2 s[14:15], s[30:31], 0xe0
	v_ashrrev_i32_e32 v14, 6, v0
	v_lshlrev_b32_e32 v0, 3, v14
	v_and_b32_e32 v0, -16, v0
	v_add_u32_e32 v3, v13, v0
	s_waitcnt lgkmcnt(0)
	s_add_u32 s12, s12, 0x1b200000
	v_and_b32_e32 v0, 3, v13
	v_lshrrev_b32_e32 v4, 2, v3
	v_lshlrev_b32_e32 v5, 1, v3
	s_addc_u32 s13, s13, 0
	v_and_or_b32 v0, v3, s17, v0
	v_and_b32_e32 v4, 4, v4
	v_and_b32_e32 v5, 24, v5
	s_add_u32 s14, s14, 0x2500000
	v_or3_b32 v0, v0, v4, v5
	v_mul_i32_i24_e32 v5, 64, v13
	s_addc_u32 s15, s15, 0
	s_ashr_i32 s41, s45, 6
	v_sub_u32_e32 v2, v2, v5
	s_ashr_i32 s44, s45, 8
	s_lshl_b32 s16, s41, 10
	v_lshlrev_b32_e32 v4, 5, v14
	v_ashrrev_i16_sdwa v2, v250, sext(v2) dst_sel:DWORD dst_unused:UNUSED_PAD src0_sel:DWORD src1_sel:BYTE_0
	v_readlane_b32 s30, v253, 57
	v_and_b32_e32 v4, 32, v4
	v_bfe_i32 v15, v2, 0, 16
	v_readlane_b32 s31, v253, 58
	s_add_u32 s36, s14, s30
	v_add_lshl_u32 v2, v4, v15, 1
	s_addc_u32 s37, s15, s31
	s_add_i32 s17, s16, 0
	v_lshl_add_u32 v0, v0, 10, v2
	s_add_i32 m0, s17, 0x10000
	v_lshl_add_u32 v134, v3, 10, v2
	global_load_lds_dwordx4 v0, s[36:37]
	s_add_i32 m0, s17, 0x12000
	s_add_u32 s30, s36, 0x20000
	global_load_lds_dwordx4 v130, s[36:37]
	s_addc_u32 s31, s37, 0
	s_add_i32 m0, s17, 0x14000
	s_load_dwordx2 s[38:39], s[38:39], 0xe0
	global_load_lds_dwordx4 v0, s[30:31]
	s_add_i32 m0, s17, 0x16000
	v_mov_b32_e32 v131, v1
	global_load_lds_dwordx4 v130, s[30:31]
	v_readlane_b32 s30, v253, 53
	v_readlane_b32 s31, v253, 54
	s_add_u32 s30, s12, s30
	s_addc_u32 s31, s13, s31
	s_add_i32 s25, s17, 0x2000
	s_mov_b32 m0, s17
	s_add_u32 s50, s30, 0x20000
	global_load_lds_dwordx4 v134, s[30:31]
	s_mov_b32 m0, s25
	s_addc_u32 s51, s31, 0
	s_add_i32 s28, s17, 0x4000
	global_load_lds_dwordx4 v132, s[30:31]
	s_mov_b32 m0, s28
	s_add_i32 s40, s17, 0x6000
	global_load_lds_dwordx4 v134, s[50:51]
	s_mov_b32 m0, s40
	v_mov_b32_e32 v135, v1
	global_load_lds_dwordx4 v132, s[50:51]
	v_mov_b32_e32 v133, v1
	s_cmp_eq_u32 s44, 1
	v_lshl_add_u64 v[8:9], s[36:37], 0, v[0:1]
	v_lshl_add_u64 v[6:7], s[36:37], 0, v[130:131]
	v_lshl_add_u64 v[2:3], s[30:31], 0, v[134:135]
	s_cselect_b64 s[52:53], -1, 0
	s_cmp_lg_u32 s44, 1
	v_lshl_add_u64 v[4:5], s[30:31], 0, v[132:133]
	s_cbranch_scc1 .LBB0_633
	s_barrier

; #define PP (kp_get())
; DI unsigned xb_ld(unsigned* p)              { return __hip_atomic_load(p, __ATOMIC_RELAXED, __HIP_MEMORY_SCOPE_AGENT); }
; #define XB_SPIN(cond, bar) do { unsigned _sp = 0; while (cond) { __builtin_amdgcn_s_sleep(1); \
;     if ((++_sp & 255u) == 0u) { if (xb_ld(&(bar)[XB_TMO])) break; if (_sp > XB_SPIN_CAP) { atomicAdd(&(bar)[XB_TMO], 1u); break; } } } } while (0)
; DI void xcd_barrier(const XcdBarrier& b) {
;     ...
;             asm volatile("s_waitcnt vmcnt(0)" ::: "memory");
;         } else {
;             XB_SPIN(xb_ld(&bar[XB_XGEN(b.x)]) == gen, bar);
;             __builtin_amdgcn_fence(__ATOMIC_ACQUIRE, "agent");
;             asm volatile("s_waitcnt vmcnt(0)" ::: "memory");
;         }
;     }
;     __syncthreads();
; __global__ void __launch_bounds__(512, 2) fwd_megakernel(Params P) {
;     ...
;         { pg8::GmArgs ga{HBUF, (const bf16_t*)(PP->ws + WS_WIN) + (size_t)NINA * DM, (const bf16_t*)(PP->ws + WS_YSSM), (long)(WS_SQ - WS_YSSM) / 2, (const bf16_t*)(PP->ws + WS_WB),
;                          (bf16_t*)(PP->ws + WS_GS), (bf16_t*)(PP->ws + WS_H2), (const float*)(PP->ws + WS_PART)};
;           pg8::SchedGM S{MTOK / 256, 4, G, c}; pg8::gemm_phase_gm(lds, ga, S); }
.LBB0_797:
	s_or_b64 exec, exec, s[38:39]
.LBB0_798:
	s_or_b64 exec, exec, s[30:31]
	s_mov_b64 s[12:13], s[0:1]
	s_waitcnt lgkmcnt(0)
	s_barrier
	s_load_dwordx2 s[62:63], s[12:13], 0xe0
	s_mov_b64 s[12:13], s[0:1]
	s_load_dwordx2 s[64:65], s[12:13], 0xe0
	s_mov_b64 s[12:13], s[0:1]
	s_load_dwordx2 s[36:37], s[12:13], 0xe0
	s_mov_b64 s[12:13], s[0:1]
	s_load_dwordx2 s[44:45], s[12:13], 0xe0
	s_mov_b64 s[12:13], s[0:1]
	s_load_dwordx2 s[30:31], s[12:13], 0xe0
	s_mov_b64 s[12:13], s[0:1]
	s_load_dwordx2 s[50:51], s[12:13], 0xe0
	s_mov_b64 s[12:13], s[0:1]
	s_load_dwordx2 s[38:39], s[12:13], 0xe0
	v_readlane_b32 s12, v252, 28
	v_mov_b32_e32 v6, v196
	v_readlane_b32 s13, v252, 29
	s_and_b64 vcc, exec, s[12:13]
	v_readfirstlane_b32 s13, v6
	s_cbranch_vccnz .LBB0_800
	v_readlane_b32 s14, v253, 55
	v_readlane_b32 s52, v253, 51
	s_mov_b32 s49, s14
	v_readlane_b32 s53, v253, 52
	v_readlane_b32 s15, v253, 56

; #define PP (kp_get())
; DI unsigned xb_ld(unsigned* p)              { return __hip_atomic_load(p, __ATOMIC_RELAXED, __HIP_MEMORY_SCOPE_AGENT); }
; #define XB_SPIN(cond, bar) do { unsigned _sp = 0; while (cond) { __builtin_amdgcn_s_sleep(1); \
;     if ((++_sp & 255u) == 0u) { if (xb_ld(&(bar)[XB_TMO])) break; if (_sp > XB_SPIN_CAP) { atomicAdd(&(bar)[XB_TMO], 1u); break; } } } } while (0)
; DI void xcd_barrier(const XcdBarrier& b) {
;     ...
;             asm volatile("s_waitcnt vmcnt(0)" ::: "memory");
;         } else {
;             XB_SPIN(xb_ld(&bar[XB_XGEN(b.x)]) == gen, bar);
;             __builtin_amdgcn_fence(__ATOMIC_ACQUIRE, "agent");
;             asm volatile("s_waitcnt vmcnt(0)" ::: "memory");
;         }
;     }
;     __syncthreads();
; __global__ void __launch_bounds__(512, 2) fwd_megakernel(Params P) {
;     ...
;         { pg8::Gemm g{(const bf16_t*)(PP->ws + WS_H2), (const bf16_t*)(PP->ws + WS_WOUT), DM, DM, DM, 0, 0}; pg8::SchedMN S{MTOK / 256, 4, G, c}; pg8::EpiResid E{xin, PP->out, HBUF, PP->norm_cross + l * DM, (float*)(PP->ws + WS_PART)}; pg8::gemm_phase(lds, g, S, E); }
.LBB0_938:
	s_or_b64 exec, exec, s[38:39]
.LBB0_939:
	s_or_b64 exec, exec, s[30:31]
	s_mov_b64 s[12:13], s[0:1]
	s_waitcnt lgkmcnt(0)
	s_barrier
	s_load_dwordx2 s[36:37], s[12:13], 0xe0
	s_mov_b64 s[12:13], s[0:1]
	s_load_dwordx2 s[38:39], s[12:13], 0xe0
	s_mov_b64 s[12:13], s[0:1]
	s_load_dwordx2 s[62:63], s[12:13], 0xd8
	s_mov_b64 s[12:13], s[0:1]
	s_load_dwordx2 s[66:67], s[12:13], 0xe0
	s_mov_b64 s[12:13], s[0:1]
	s_load_dwordx2 s[50:51], s[12:13], 0x90
	s_mov_b64 s[12:13], s[0:1]
	s_load_dwordx2 s[44:45], s[12:13], 0xe0
	v_readlane_b32 s12, v252, 28
	v_mov_b32_e32 v16, v196
	v_readlane_b32 s13, v252, 29
	s_and_b64 vcc, exec, s[12:13]
	v_readfirstlane_b32 s28, v16
	s_cbranch_vccnz .LBB0_941
	v_readlane_b32 s82, v253, 55
	v_readlane_b32 s30, v253, 51
	v_readlane_b32 s83, v253, 56
	v_readlane_b32 s31, v253, 52

; #define PP (kp_get())
; DI unsigned xb_ld(unsigned* p)              { return __hip_atomic_load(p, __ATOMIC_RELAXED, __HIP_MEMORY_SCOPE_AGENT); }
; #define XB_SPIN(cond, bar) do { unsigned _sp = 0; while (cond) { __builtin_amdgcn_s_sleep(1); \
;     if ((++_sp & 255u) == 0u) { if (xb_ld(&(bar)[XB_TMO])) break; if (_sp > XB_SPIN_CAP) { atomicAdd(&(bar)[XB_TMO], 1u); break; } } } } while (0)
; DI void xcd_barrier(const XcdBarrier& b) {
;     ...
;             asm volatile("s_waitcnt vmcnt(0)" ::: "memory");
;         } else {
;             XB_SPIN(xb_ld(&bar[XB_XGEN(b.x)]) == gen, bar);
;             __builtin_amdgcn_fence(__ATOMIC_ACQUIRE, "agent");
;             asm volatile("s_waitcnt vmcnt(0)" ::: "memory");
;         }
;     }
;     __syncthreads();
; __global__ void __launch_bounds__(512, 2) fwd_megakernel(Params P) {
;     ...
;         { pg8::Gemm g{HBUF, (const bf16_t*)(PP->ws + WS_WXQ), DM, DM, DM, 0, 0}; pg8::SchedMN S{MTOK / 256, 2, G, c};
;           pg8::EpiBf16<0, true> E{(bf16_t*)(PP->ws + WS_XQ), 512, 0.12751743074602334f, (const float*)(PP->ws + WS_PART)}; pg8::gemm_phase(lds, g, S, E); }
.LBB0_1028:
	s_or_b64 exec, exec, s[38:39]
.LBB0_1029:
	s_or_b64 exec, exec, s[30:31]
	s_mov_b64 s[12:13], s[0:1]
	s_waitcnt lgkmcnt(0)
	s_barrier
	s_load_dwordx2 s[30:31], s[12:13], 0xe0
	s_mov_b64 s[12:13], s[0:1]
	s_load_dwordx2 s[44:45], s[12:13], 0xe0
	s_mov_b64 s[12:13], s[0:1]
	s_load_dwordx2 s[36:37], s[12:13], 0xe0
	s_mov_b64 s[12:13], s[0:1]
	s_load_dwordx2 s[38:39], s[12:13], 0xe0
	v_mov_b32_e32 v10, v196
	s_and_b64 vcc, exec, s[94:95]
	v_readfirstlane_b32 s49, v10
	s_cbranch_vccnz .LBB0_1031
	v_readlane_b32 s12, v253, 0
	s_mov_b32 s62, s12
	v_readlane_b32 s12, v253, 1
	s_mov_b32 s64, s12

; #define PP (kp_get())
; DI unsigned xb_ld(unsigned* p)              { return __hip_atomic_load(p, __ATOMIC_RELAXED, __HIP_MEMORY_SCOPE_AGENT); }
; #define XB_SPIN(cond, bar) do { unsigned _sp = 0; while (cond) { __builtin_amdgcn_s_sleep(1); \
;     if ((++_sp & 255u) == 0u) { if (xb_ld(&(bar)[XB_TMO])) break; if (_sp > XB_SPIN_CAP) { atomicAdd(&(bar)[XB_TMO], 1u); break; } } } } while (0)
; DI void xcd_barrier(const XcdBarrier& b) {
;     ...
;             asm volatile("s_waitcnt vmcnt(0)" ::: "memory");
;         } else {
;             XB_SPIN(xb_ld(&bar[XB_XGEN(b.x)]) == gen, bar);
;             __builtin_amdgcn_fence(__ATOMIC_ACQUIRE, "agent");
;             asm volatile("s_waitcnt vmcnt(0)" ::: "memory");
;         }
;     }
;     __syncthreads();
; __global__ void __launch_bounds__(512, 2) fwd_megakernel(Params P) {
;     ...
;         for (int idx = c; idx < 512; idx += G) { const int qb = idx & 15, bh = idx >> 4, b = bh >> 2, hh = bh & 3;
;             const bf16_t* kb = (const bf16_t*)(PP->ws + WS_MEMKV) + (size_t)(l * 2) * 2048 * 512 + (size_t)b * MEML * 512 + hh * 128;
;             attn2_unit<false>(qb, (const bf16_t*)(PP->ws + WS_XQ) + (size_t)b * SEQ * 512 + hh * 128, (bf16_t*)(PP->ws + WS_XQ) + (size_t)b * SEQ * 512 + hh * 128, kb, kb + (size_t)2048 * 512, 4, 0.f, nullptr, 1.f, lds); }
.LBB0_1125:
	s_or_b64 exec, exec, s[38:39]
.LBB0_1126:
	s_or_b64 exec, exec, s[30:31]
	v_readlane_b32 s12, v252, 28
	v_readlane_b32 s13, v252, 29
	s_and_b64 vcc, exec, s[12:13]
	s_mov_b64 s[50:51], 0x9a00000
	s_waitcnt lgkmcnt(0)
	s_barrier
	s_cbranch_vccnz .LBB0_1186
	s_lshl_b32 s12, s48, 21
	s_lshl_b32 s12, s12, 1
	v_readlane_b32 s13, v251, 0
	s_mov_b32 s14, s2
	s_branch .LBB0_1129

; #define PP (kp_get())
; DI unsigned xb_ld(unsigned* p)              { return __hip_atomic_load(p, __ATOMIC_RELAXED, __HIP_MEMORY_SCOPE_AGENT); }
; #define XB_SPIN(cond, bar) do { unsigned _sp = 0; while (cond) { __builtin_amdgcn_s_sleep(1); \
;     if ((++_sp & 255u) == 0u) { if (xb_ld(&(bar)[XB_TMO])) break; if (_sp > XB_SPIN_CAP) { atomicAdd(&(bar)[XB_TMO], 1u); break; } } } } while (0)
; DI void xcd_barrier(const XcdBarrier& b) {
;     ...
;             asm volatile("s_waitcnt vmcnt(0)" ::: "memory");
;         } else {
;             XB_SPIN(xb_ld(&bar[XB_XGEN(b.x)]) == gen, bar);
;             __builtin_amdgcn_fence(__ATOMIC_ACQUIRE, "agent");
;             asm volatile("s_waitcnt vmcnt(0)" ::: "memory");
;         }
;     }
;     __syncthreads();
; __global__ void __launch_bounds__(512, 2) fwd_megakernel(Params P) {
;     ...
;         { pg8::Gemm g{(const bf16_t*)(PP->ws + WS_XQ), (const bf16_t*)(PP->ws + WS_WXO), 512, 512, 512, 0, 0}; pg8::SchedMN S{MTOK / 256, 4, G, c}; pg8::EpiResid E{PP->out, PP->out, HBUF, PP->norm_mlp + l * DM, (float*)(PP->ws + WS_PART)}; pg8::gemm_phase(lds, g, S, E); }
.LBB0_1237:
	s_or_b64 exec, exec, s[38:39]
.LBB0_1238:
	s_or_b64 exec, exec, s[30:31]
	s_mov_b64 s[12:13], s[0:1]
	s_waitcnt lgkmcnt(0)
	s_barrier
	s_load_dwordx2 s[36:37], s[12:13], 0xe0
	s_mov_b64 s[12:13], s[0:1]
	s_load_dwordx2 s[38:39], s[12:13], 0xe0
	s_mov_b64 s[12:13], s[0:1]
	s_load_dwordx2 s[30:31], s[12:13], 0xd8
	s_mov_b64 s[12:13], s[0:1]
	s_load_dwordx2 s[48:49], s[12:13], 0xd8
	s_mov_b64 s[12:13], s[0:1]
	s_load_dwordx2 s[64:65], s[12:13], 0xe0
	s_mov_b64 s[12:13], s[0:1]
	s_load_dwordx2 s[66:67], s[12:13], 0xb8
	s_mov_b64 s[12:13], s[0:1]
	s_load_dwordx2 s[50:51], s[12:13], 0xe0
	v_readlane_b32 s12, v252, 28
	v_mov_b32_e32 v16, v196
	v_readlane_b32 s13, v252, 29
	s_and_b64 vcc, exec, s[12:13]
	v_readfirstlane_b32 s28, v16
	s_cbranch_vccnz .LBB0_1240
	v_readlane_b32 s78, v253, 55
	v_readlane_b32 s44, v253, 51
	v_readlane_b32 s79, v253, 56
	v_readlane_b32 s45, v253, 52

; #define PP (kp_get())
; DI unsigned xb_ld(unsigned* p)              { return __hip_atomic_load(p, __ATOMIC_RELAXED, __HIP_MEMORY_SCOPE_AGENT); }
; #define XB_SPIN(cond, bar) do { unsigned _sp = 0; while (cond) { __builtin_amdgcn_s_sleep(1); \
;     if ((++_sp & 255u) == 0u) { if (xb_ld(&(bar)[XB_TMO])) break; if (_sp > XB_SPIN_CAP) { atomicAdd(&(bar)[XB_TMO], 1u); break; } } } } while (0)
; DI void xcd_barrier(const XcdBarrier& b) {
;     ...
;             asm volatile("s_waitcnt vmcnt(0)" ::: "memory");
;         } else {
;             XB_SPIN(xb_ld(&bar[XB_XGEN(b.x)]) == gen, bar);
;             __builtin_amdgcn_fence(__ATOMIC_ACQUIRE, "agent");
;             asm volatile("s_waitcnt vmcnt(0)" ::: "memory");
;         }
;     }
;     __syncthreads();
; __global__ void __launch_bounds__(512, 2) fwd_megakernel(Params P) {
;     ...
;         { pg8::Gemm g{HBUF, (const bf16_t*)(PP->ws + WS_WUP), DM, DM, DM, 0, 0}; pg8::SchedMN S{MTOK / 256, 16, G, c};
;           pg8::EpiBf16<2, true> E{(bf16_t*)(PP->ws + WS_HID), 4096, 1.f, (const float*)(PP->ws + WS_PART)}; pg8::gemm_phase(lds, g, S, E); }
.LBB0_1327:
	s_or_b64 exec, exec, s[38:39]
.LBB0_1328:
	s_or_b64 exec, exec, s[30:31]
	s_mov_b64 s[12:13], s[0:1]
	s_waitcnt lgkmcnt(0)
	s_barrier
	s_load_dwordx2 s[36:37], s[12:13], 0xe0
	s_mov_b64 s[12:13], s[0:1]
	s_load_dwordx2 s[50:51], s[12:13], 0xe0
	s_mov_b64 s[12:13], s[0:1]
	s_load_dwordx2 s[44:45], s[12:13], 0xe0
	s_mov_b64 s[12:13], s[0:1]
	s_load_dwordx2 s[38:39], s[12:13], 0xe0
	v_readlane_b32 s12, v252, 62
	v_readlane_b32 s13, v252, 63
	v_mov_b32_e32 v10, v196
	s_andn2_b64 vcc, exec, s[12:13]
	v_cndmask_b32_e64 v0, 0, 1, s[12:13]
	v_cmp_ne_u32_e64 s[68:69], 1, v0
	v_readfirstlane_b32 s64, v10
	s_cbranch_vccnz .LBB0_1330
	v_readlane_b32 s12, v253, 3
	s_mov_b32 s30, s12
	v_readlane_b32 s12, v253, 4
	s_mov_b32 s48, s12

; #define PP (kp_get())
; DI unsigned xb_ld(unsigned* p)              { return __hip_atomic_load(p, __ATOMIC_RELAXED, __HIP_MEMORY_SCOPE_AGENT); }
; #define XB_SPIN(cond, bar) do { unsigned _sp = 0; while (cond) { __builtin_amdgcn_s_sleep(1); \
;     if ((++_sp & 255u) == 0u) { if (xb_ld(&(bar)[XB_TMO])) break; if (_sp > XB_SPIN_CAP) { atomicAdd(&(bar)[XB_TMO], 1u); break; } } } } while (0)
; DI void xcd_barrier(const XcdBarrier& b) {
;     ...
;             asm volatile("s_waitcnt vmcnt(0)" ::: "memory");
;         } else {
;             XB_SPIN(xb_ld(&bar[XB_XGEN(b.x)]) == gen, bar);
;             __builtin_amdgcn_fence(__ATOMIC_ACQUIRE, "agent");
;             asm volatile("s_waitcnt vmcnt(0)" ::: "memory");
;         }
;     }
;     __syncthreads();
; __global__ void __launch_bounds__(512, 2) fwd_megakernel(Params P) {
;     ...
;         { pg8::Gemm g{(const bf16_t*)(PP->ws + WS_HID), (const bf16_t*)(PP->ws + WS_WDN), 4096, 4096, 4096, 0, 0}; pg8::SchedMN S{MTOK / 256, 4, G, c}; pg8::EpiResid E{PP->out, PP->out, HBUF, PP->norm_mix + (l + 1 < DEPTH ? l + 1 : l) * DM, (float*)(PP->ws + WS_PART)}; pg8::gemm_phase(lds, g, S, E); }
.LBB0_1424:
	s_or_b64 exec, exec, s[38:39]
.LBB0_1425:
	s_or_b64 exec, exec, s[30:31]
	s_mov_b64 s[12:13], s[0:1]
	s_waitcnt lgkmcnt(0)
	s_barrier
	s_load_dwordx2 s[36:37], s[12:13], 0xe0
	s_mov_b64 s[12:13], s[0:1]
	s_load_dwordx2 s[38:39], s[12:13], 0xe0
	s_mov_b64 s[12:13], s[0:1]
	s_load_dwordx2 s[30:31], s[12:13], 0xd8
	s_mov_b64 s[12:13], s[0:1]
	s_load_dwordx2 s[48:49], s[12:13], 0xd8
	s_mov_b64 s[12:13], s[0:1]
	s_load_dwordx2 s[62:63], s[12:13], 0xe0
	s_mov_b64 s[12:13], s[0:1]
	s_load_dwordx2 s[64:65], s[12:13], 0x18
	s_mov_b64 s[12:13], s[0:1]
	s_load_dwordx2 s[50:51], s[12:13], 0xe0
	v_readlane_b32 s12, v252, 28
	v_mov_b32_e32 v16, v196
	v_readlane_b32 s13, v252, 29
	s_and_b64 vcc, exec, s[12:13]
	v_readfirstlane_b32 s28, v16
	s_cbranch_vccnz .LBB0_1427
	v_readlane_b32 s78, v253, 55
	v_readlane_b32 s44, v253, 51
	v_readlane_b32 s79, v253, 56
	v_readlane_b32 s45, v253, 52
